# speedup vs baseline: 1.0013x; 1.0013x over previous
; __device__ __forceinline__ bf16x8 cat44(s16x4 a, s16x4 b) { return (bf16x8){a[0], a[1], a[2], a[3], b[0], b[1], b[2], b[3]}; }
; __device__ __forceinline__ void ssd_out_item(KP P, int l, int seq, int c, int g, char* smem) {
;     ...
;       cacc = __builtin_amdgcn_mfma_f32_16x16x32_bf16(as_bf16x8(av), as_bf16x8(bv), cacc, 0, 0, 0);
;     }
; #pragma unroll
;     for (int j = 0; j < 4; ++j) CBs[(lb * 16 + fq * 4 + j) * 65 + sb * 16 + fr] = cacc[j];
;   }
; #pragma unroll
;   for (int i = 0; i < 8; ++i) {
;     const int tok = i * 8 + (lane >> 3), vec = lane & 7;
;     uint4 v = make_uint4(zz, zz, zz, zz);
;     if (tok < L) v = *(const uint4*)(XBC + (long)(rb + tok) * 3072 + h * 64 + vec * 8);
;     *(uint4*)(Xs + tok * 72 + vec * 8) = v;
;   }
;   __syncthreads();
;   f32x4 accy[4][4] = {}, acco[4][4] = {};
;   const int trr = fq * 8 + ((lane >> 2) & 3), trc = (lane & 3) * 4;
; #pragma unroll
;   for (int ks = 0; ks < 2; ++ks) {
;     bf16x8 bfr[4];
; #pragma unroll
;     for (int nb = 0; nb < 4; ++nb) {
;       const u16* p0 = Xs + (ks * 32 + trr) * 72 + nb * 16 + trc;
;       bfr[nb] = cat44(ldtr(p0), ldtr(p0 + 4 * 72));
;     }
; #pragma unroll
;     for (int mb = 0; mb < 4; ++mb) {
;       if (ks * 32 > mb * 16 + 15) continue;
;       const int lrow = mb * 16 + fr;
;       const float al = acs[lrow];
;       float gv[8];
; #pragma unroll
;       for (int i = 0; i < 8; ++i) {
;         const int s = ks * 32 + fq * 8 + i;
;         const float d = fminf(al - acs[s], 0.f);
;         gv[i] = (s <= lrow) ? CBs[lrow * 65 + s] * __expf(d) * dts[s] : 0.f;
.LBB0_944:
	s_or_b64 exec, exec, s[0:1]
	global_load_dwordx4 v[16:19], v[18:19], off offset:192
	s_movk_i32 s0, 0x2400
	v_mul_lo_u32 v0, v22, s0
	v_add_u32_e32 v172, 0, v0
	v_lshlrev_b32_e32 v0, 4, v20
	s_movk_i32 s4, 0x1800
	v_lshl_add_u32 v25, v170, 2, v173
	v_cmp_le_u32_e32 vcc, v69, v170
	v_mov_b32_e32 v35, 0
	v_lshlrev_b32_e32 v26, 2, v69
	v_mov_b32_e32 v36, 0
	s_waitcnt vmcnt(0)
	v_mfma_f32_16x16x32_bf16 v[8:11], v[8:11], v[16:19], v[12:15]
	s_nop 2
	v_lshrrev_b32_e32 v14, 3, v21
	v_or_b32_e32 v15, s14, v14
	s_nop 2
	ds_write2_b32 v23, v8, v9 offset0:16 offset1:81
	ds_write2_b32 v23, v10, v11 offset0:146 offset1:211
	v_and_b32_e32 v8, 0x70, v0
	v_lshlrev_b32_e32 v0, 6, v64
	v_ashrrev_i32_e32 v1, 31, v0
	v_lshl_add_u64 v[10:11], v[0:1], 1, s[10:11]
	v_mov_b32_e32 v9, v3
	v_lshl_add_u64 v[12:13], v[10:11], 0, v[8:9]
	v_mad_i64_i32 v[10:11], s[0:1], v15, s4, v[12:13]
	v_mul_u32_u24_e32 v9, 0x90, v14
	v_add3_u32 v14, v172, v8, v9
	global_load_dwordx4 v[208:211], v[10:11], off
	v_or_b32_e32 v8, 8, v15
	v_mad_i64_i32 v[8:9], s[0:1], v8, s4, v[12:13]
	global_load_dwordx4 v[212:215], v[8:9], off
	v_or_b32_e32 v8, 16, v15
	v_mad_i64_i32 v[8:9], s[0:1], v8, s4, v[12:13]
	global_load_dwordx4 v[216:219], v[8:9], off
	v_or_b32_e32 v8, 24, v15
	v_mad_i64_i32 v[8:9], s[0:1], v8, s4, v[12:13]
	global_load_dwordx4 v[176:179], v[8:9], off
	s_waitcnt vmcnt(3)
	ds_write_b128 v14, v[208:211] offset:22784
	s_waitcnt vmcnt(2)
	ds_write_b128 v14, v[212:215] offset:23936
	s_waitcnt vmcnt(1)
	ds_write_b128 v14, v[216:219] offset:25088
	s_waitcnt vmcnt(0)
	ds_write_b128 v14, v[176:179] offset:26240
	v_or_b32_e32 v8, 32, v15
	v_mad_i64_i32 v[8:9], s[0:1], v8, s4, v[12:13]
	global_load_dwordx4 v[208:211], v[8:9], off
	v_or_b32_e32 v8, 40, v15
	v_mad_i64_i32 v[8:9], s[0:1], v8, s4, v[12:13]
	global_load_dwordx4 v[212:215], v[8:9], off
	v_or_b32_e32 v8, 48, v15
	v_mad_i64_i32 v[8:9], s[0:1], v8, s4, v[12:13]
	global_load_dwordx4 v[216:219], v[8:9], off
	v_or_b32_e32 v8, 56, v15
	v_mad_i64_i32 v[8:9], s[0:1], v8, s4, v[12:13]
	global_load_dwordx4 v[176:179], v[8:9], off
	s_waitcnt vmcnt(3)
	ds_write_b128 v14, v[208:211] offset:27392
	s_waitcnt vmcnt(2)
	ds_write_b128 v14, v[212:215] offset:28544
	s_waitcnt vmcnt(1)
	ds_write_b128 v14, v[216:219] offset:29696
	s_waitcnt vmcnt(0)
	ds_write_b128 v14, v[176:179] offset:30848
	s_movk_i32 s0, 0x90
	v_lshlrev_b32_e32 v9, 3, v20
	v_lshrrev_b32_e32 v8, 2, v20
	v_and_b32_e32 v9, 24, v9
	v_add_u32_e32 v32, v172, v9
	v_and_or_b32 v24, v8, 3, v69
	v_mad_u32_u24 v14, v24, s0, v32
	s_waitcnt lgkmcnt(0)
	s_barrier
	ds_read_b64_tr_b16 v[20:21], v14 offset:22784
	ds_read_b64_tr_b16 v[16:17], v14 offset:22816
	ds_read_b64_tr_b16 v[22:23], v14 offset:23360
	ds_read_b64_tr_b16 v[18:19], v14 offset:23392
	ds_read_b64_tr_b16 v[8:9], v14 offset:22848
	ds_read_b64_tr_b16 v[10:11], v14 offset:23424
	ds_read_b64_tr_b16 v[12:13], v14 offset:22880
	ds_read_b64_tr_b16 v[14:15], v14 offset:23456
	ds_read_b32 v37, v25 offset:16640
	s_movk_i32 s0, 0x104
	v_mad_u32_u24 v27, v170, s0, 0
	s_and_saveexec_b64 s[0:1], vcc
	s_cbranch_execz .LBB0_946
	v_add_u32_e32 v28, v173, v26
	ds_read2st64_b32 v[28:29], v28 offset0:65 offset1:73
	v_add_u32_e32 v30, v27, v26
	ds_read_b32 v30, v30
	s_waitcnt lgkmcnt(1)
	v_sub_f32_e32 v28, v37, v28
	v_min_f32_e32 v28, 0, v28
	v_mul_f32_e32 v28, 0x3fb8aa3b, v28
	v_exp_f32_e32 v28, v28
	s_waitcnt lgkmcnt(0)
	v_mul_f32_e32 v28, v30, v28
	v_mul_f32_e32 v36, v29, v28

; __device__ __forceinline__ void ssd_out_item(KP P, int l, int seq, int c, int g, char* smem) {
;     ...
;         const float d = fminf(al - acs[s], 0.f);
;         gv[i] = (s <= lrow) ? CBs[lrow * 65 + s] * __expf(d) * dts[s] : 0.f;
;       }
;       const bf16x8 af = as_bf16x8(pack8(gv));
; #pragma unroll
;       for (int nb = 0; nb < 4; ++nb) accy[mb][nb] = __builtin_amdgcn_mfma_f32_16x16x32_bf16(af, bfr[nb], accy[mb][nb], 0, 0, 0);
;     }
;   }
;   const float* hin = P->st_ssm + ((long)(l * 8 + (isS ? seq - 2 : 0)) * 32 + h) * 8192;
;   const u16* hin16 = (const u16*)(ws + WS_ST) + ((long)((isS ? 0 : seq) * 64 + c) * 32 + h) * 8192;
; #pragma unroll
;   for (int ks = 0; ks < 4; ++ks) {
;     bf16x8 cf[4], hf[4];
; #pragma unroll
;     for (int mb = 0; mb < 4; ++mb) {
;       const int tl = mb * 16 + fr;
;       uint4 av = make_uint4(zz, zz, zz, zz);
;       if (tl < L) av = *(const uint4*)(XBC + (long)(rb + tl) * 3072 + 2560 + g * 128 + ks * 32 + fq * 8);
;       cf[mb] = as_bf16x8(av);
;     }
; #pragma unroll
;     for (int nb = 0; nb < 4; ++nb) {
;       if (isS) {
;         const float* hp = hin + (nb * 16 + fr) * 128 + ks * 32 + fq * 8;
;         const float4 h0 = *(const float4*)hp, h1 = *(const float4*)(hp + 4);
;         float f[8] = {h0.x, h0.y, h0.z, h0.w, h1.x, h1.y, h1.z, h1.w};
;         hf[nb] = as_bf16x8(pack8(f));
;       } else {
;         hf[nb] = as_bf16x8(*(const uint4*)(hin16 + (nb * 16 + fr) * 128 + ks * 32 + fq * 8));
;       }
;     }
; #pragma unroll
;     for (int mb = 0; mb < 4; ++mb)
; #pragma unroll
;       for (int nb = 0; nb < 4; ++nb) acco[mb][nb] = __builtin_amdgcn_mfma_f32_16x16x32_bf16(cf[mb], hf[nb], acco[mb][nb], 0, 0, 0);
.LBB0_1008:
	s_or_b64 exec, exec, s[0:1]
	v_bfe_u32 v67, v58, 16, 1
	v_add3_u32 v58, v58, v67, s33
	v_bfe_u32 v67, v57, 16, 1
	v_lshrrev_b32_e32 v58, 16, v58
	v_add3_u32 v57, v57, v67, s33
	v_and_or_b32 v58, v57, s30, v58
	v_bfe_u32 v57, v60, 16, 1
	v_add3_u32 v57, v60, v57, s33
	v_bfe_u32 v60, v59, 16, 1
	v_lshrrev_b32_e32 v57, 16, v57
	v_add3_u32 v59, v59, v60, s33
	v_and_or_b32 v59, v59, s30, v57
	v_bfe_u32 v57, v62, 16, 1
	v_add3_u32 v57, v62, v57, s33
	v_bfe_u32 v60, v61, 16, 1
	v_lshrrev_b32_e32 v57, 16, v57
	v_add3_u32 v60, v61, v60, s33
	v_and_or_b32 v60, v60, s30, v57
	v_bfe_u32 v57, v66, 16, 1
	v_add3_u32 v57, v66, v57, s33
	v_bfe_u32 v61, v63, 16, 1
	v_lshrrev_b32_e32 v57, 16, v57
	v_add3_u32 v61, v63, v61, s33
	v_and_or_b32 v61, v61, s30, v57
	s_lshl_b32 s0, s15, 6
	s_or_b32 s0, s0, s20
	s_ashr_i32 s1, s0, 31
	s_lshl_b64 s[0:1], s[0:1], 19
	s_add_u32 s0, s8, s0
	v_mfma_f32_16x16x32_bf16 v[16:19], v[58:61], v[12:15], v[16:19]
	s_addc_u32 s1, s9, s1
	s_movk_i32 s5, 0x1800
	s_movk_i32 s4, 0x1000
	v_mfma_f32_16x16x32_bf16 v[12:15], v[58:61], v[32:35], v[8:11]
	v_or_b32_e32 v32, s14, v88
	v_mfma_f32_16x16x32_bf16 v[8:11], v[58:61], v[36:39], v[24:27]
	v_mov_b64_e32 v[36:37], s[10:11]
	v_or_b32_e32 v38, s14, v56
	s_nop 0
	v_lshlrev_b64 v[24:25], 14, v[64:65]
	v_lshl_add_u64 v[24:25], s[0:1], 0, v[24:25]
	v_mfma_f32_16x16x32_bf16 v[20:23], v[58:61], v[28:31], v[20:23]
	v_lshl_add_u64 v[58:59], v[24:25], 0, v[2:3]
	v_mad_i64_i32 v[24:25], s[0:1], v68, s5, v[36:37]
	v_lshl_add_u64 v[24:25], v[24:25], 0, s[26:27]
	v_or_b32_e32 v28, s14, v70
	v_lshl_add_u64 v[24:25], v[24:25], 0, v[2:3]
	v_mad_i64_i32 v[28:29], s[0:1], v28, s5, v[36:37]
	v_add_co_u32_e32 v102, vcc, s4, v24
	v_lshl_add_u64 v[28:29], v[28:29], 0, s[26:27]
	s_nop 0
	v_addc_co_u32_e32 v103, vcc, 0, v25, vcc
	v_lshl_add_u64 v[28:29], v[28:29], 0, v[2:3]
	v_mad_i64_i32 v[32:33], s[0:1], v32, s5, v[36:37]
	v_add_co_u32_e32 v212, vcc, s4, v28
	v_lshl_add_u64 v[32:33], v[32:33], 0, s[26:27]
	s_nop 0
	v_addc_co_u32_e32 v213, vcc, 0, v29, vcc
	v_lshl_add_u64 v[32:33], v[32:33], 0, v[2:3]
	v_mad_i64_i32 v[36:37], s[0:1], v38, s5, v[36:37]
	v_add_co_u32_e32 v214, vcc, s4, v32
	v_lshl_add_u64 v[36:37], v[36:37], 0, s[26:27]
	s_nop 0
	v_addc_co_u32_e32 v215, vcc, 0, v33, vcc
	v_lshl_add_u64 v[36:37], v[36:37], 0, v[2:3]
	v_lshlrev_b32_e32 v2, 8, v170
	v_add_co_u32_e32 v216, vcc, s4, v36
	v_lshl_add_u64 v[64:65], v[58:59], 0, v[2:3]
	s_mov_b64 s[0:1], 0x45064000
	v_addc_co_u32_e32 v217, vcc, 0, v37, vcc
	v_lshl_add_u64 v[218:219], v[64:65], 0, s[0:1]
	s_mov_b32 s0, 0x45065000
	v_add_co_u32_e32 v92, vcc, s0, v64
	s_mov_b32 s0, 0x45066000
	s_nop 0
	v_addc_co_u32_e32 v93, vcc, 0, v65, vcc
	global_load_dwordx4 v[24:27], v[102:103], off offset:1024
	global_load_dwordx4 v[28:31], v[212:213], off offset:1024
	global_load_dwordx4 v[32:35], v[214:215], off offset:1024
	global_load_dwordx4 v[36:39], v[216:217], off offset:1024
	v_add_co_u32_e32 v88, vcc, s0, v64
	s_mov_b32 s0, 0x45067000
	s_nop 0
	v_addc_co_u32_e32 v89, vcc, 0, v65, vcc
	v_add_co_u32_e32 v90, vcc, s0, v64
	global_load_dwordx4 v[56:59], v[92:93], off offset:-4096
	global_load_dwordx4 v[60:63], v[92:93], off
	v_addc_co_u32_e32 v91, vcc, 0, v65, vcc
	global_load_dwordx4 v[64:67], v[90:91], off offset:-4096
	global_load_dwordx4 v[68:71], v[90:91], off
	v_cmp_eq_u32_e64 s[4:5], 0, v170
	s_waitcnt vmcnt(3)
	v_mfma_f32_16x16x32_bf16 v[94:97], v[24:27], v[56:59], 0
	s_waitcnt vmcnt(2)
	v_mfma_f32_16x16x32_bf16 v[98:101], v[24:27], v[60:63], 0
	s_waitcnt vmcnt(1)
	v_mfma_f32_16x16x32_bf16 v[120:123], v[24:27], v[64:67], 0
	s_waitcnt vmcnt(0)
	v_mfma_f32_16x16x32_bf16 v[24:27], v[24:27], v[68:71], 0
	v_mfma_f32_16x16x32_bf16 v[124:127], v[28:31], v[56:59], 0
	v_mfma_f32_16x16x32_bf16 v[128:131], v[28:31], v[60:63], 0
	v_mfma_f32_16x16x32_bf16 v[132:135], v[28:31], v[64:67], 0
	v_mfma_f32_16x16x32_bf16 v[28:31], v[28:31], v[68:71], 0
	v_mfma_f32_16x16x32_bf16 v[136:139], v[32:35], v[56:59], 0
	v_mfma_f32_16x16x32_bf16 v[140:143], v[32:35], v[60:63], 0
	v_mfma_f32_16x16x32_bf16 v[144:147], v[32:35], v[64:67], 0
	v_mfma_f32_16x16x32_bf16 v[32:35], v[32:35], v[68:71], 0
	v_mfma_f32_16x16x32_bf16 v[56:59], v[36:39], v[56:59], 0
	v_mfma_f32_16x16x32_bf16 v[60:63], v[36:39], v[60:63], 0
	v_mfma_f32_16x16x32_bf16 v[64:67], v[36:39], v[64:67], 0
	v_mfma_f32_16x16x32_bf16 v[36:39], v[36:39], v[68:71], 0
	global_load_dwordx4 v[68:71], v[102:103], off offset:1088
	global_load_dwordx4 v[148:151], v[212:213], off offset:1088
	global_load_dwordx4 v[152:155], v[214:215], off offset:1088
	global_load_dwordx4 v[156:159], v[216:217], off offset:1088
	global_load_dwordx4 v[160:163], v[218:219], off offset:64
	global_load_dwordx4 v[164:167], v[92:93], off offset:64
	global_load_dwordx4 v[176:179], v[88:89], off offset:64
	global_load_dwordx4 v[180:183], v[90:91], off offset:64
	s_waitcnt vmcnt(3)
	v_mfma_f32_16x16x32_bf16 v[94:97], v[68:71], v[160:163], v[94:97]
	s_waitcnt vmcnt(2)
	v_mfma_f32_16x16x32_bf16 v[98:101], v[68:71], v[164:167], v[98:101]
	s_waitcnt vmcnt(1)
	v_mfma_f32_16x16x32_bf16 v[120:123], v[68:71], v[176:179], v[120:123]
	s_waitcnt vmcnt(0)
; __device__ __forceinline__ float bf2f(u16 h) { return __uint_as_float(((unsigned)h) << 16); }
; __device__ __forceinline__ void ssd_out_item(KP P, int l, int seq, int c, int g, char* smem) {
;     ...
; #pragma unroll
;     for (int mb = 0; mb < 4; ++mb)
; #pragma unroll
;       for (int nb = 0; nb < 4; ++nb) acco[mb][nb] = __builtin_amdgcn_mfma_f32_16x16x32_bf16(cf[mb], hf[nb], acco[mb][nb], 0, 0, 0);
;   }
;   const float Dh = P->ssm_d[l * 32 + h];
; #pragma unroll
;   for (int mb = 0; mb < 4; ++mb) {
; #pragma unroll
;     for (int j = 0; j < 4; ++j) {
;       const int lr = mb * 16 + fq * 4 + j;
;       const float ea = __expf(acs[lr]);
;       float ssq = 0.f;
; #pragma unroll
;       for (int nb = 0; nb < 4; ++nb) {
;         const int p = nb * 16 + fr;
;         float y = accy[mb][nb][j] + ea * acco[mb][nb][j] + Dh * bf2f(Xs[lr * 72 + p]);
;         float z = 0.f;
;         if (lr < L) z = bf2f(PROJ[(long)(rb + lr) * NC + OZ + h * 64 + p]);
	v_mfma_f32_16x16x32_bf16 v[68:71], v[68:71], v[180:183], v[24:27]
	v_mfma_f32_16x16x32_bf16 v[124:127], v[148:151], v[160:163], v[124:127]
	v_mfma_f32_16x16x32_bf16 v[128:131], v[148:151], v[164:167], v[128:131]
	v_mfma_f32_16x16x32_bf16 v[132:135], v[148:151], v[176:179], v[132:135]
	v_mfma_f32_16x16x32_bf16 v[148:151], v[148:151], v[180:183], v[28:31]
	v_mfma_f32_16x16x32_bf16 v[136:139], v[152:155], v[160:163], v[136:139]
	v_mfma_f32_16x16x32_bf16 v[140:143], v[152:155], v[164:167], v[140:143]
	v_mfma_f32_16x16x32_bf16 v[144:147], v[152:155], v[176:179], v[144:147]
	v_mfma_f32_16x16x32_bf16 v[152:155], v[152:155], v[180:183], v[32:35]
	v_mfma_f32_16x16x32_bf16 v[160:163], v[156:159], v[160:163], v[56:59]
	v_mfma_f32_16x16x32_bf16 v[164:167], v[156:159], v[164:167], v[60:63]
	v_mfma_f32_16x16x32_bf16 v[176:179], v[156:159], v[176:179], v[64:67]
	v_mfma_f32_16x16x32_bf16 v[180:183], v[156:159], v[180:183], v[36:39]
	s_nop 2
	global_load_dwordx4 v[36:39], v[102:103], off offset:1152
	global_load_dwordx4 v[156:159], v[212:213], off offset:1152
	global_load_dwordx4 v[184:187], v[214:215], off offset:1152
	global_load_dwordx4 v[192:195], v[216:217], off offset:1152
	global_load_dwordx4 v[196:199], v[218:219], off offset:128
	global_load_dwordx4 v[200:203], v[92:93], off offset:128
	global_load_dwordx4 v[204:207], v[88:89], off offset:128
	global_load_dwordx4 v[208:211], v[90:91], off offset:128
	s_waitcnt vmcnt(3)
	v_mfma_f32_16x16x32_bf16 v[24:27], v[36:39], v[196:199], v[94:97]
	s_waitcnt vmcnt(2)
	v_mfma_f32_16x16x32_bf16 v[28:31], v[36:39], v[200:203], v[98:101]
	s_waitcnt vmcnt(1)
	v_mfma_f32_16x16x32_bf16 v[32:35], v[36:39], v[204:207], v[120:123]
	s_waitcnt vmcnt(0)
	v_mfma_f32_16x16x32_bf16 v[36:39], v[36:39], v[208:211], v[68:71]
	v_mfma_f32_16x16x32_bf16 v[56:59], v[156:159], v[196:199], v[124:127]
	v_mfma_f32_16x16x32_bf16 v[60:63], v[156:159], v[200:203], v[128:131]
	v_mfma_f32_16x16x32_bf16 v[64:67], v[156:159], v[204:207], v[132:135]
	v_mfma_f32_16x16x32_bf16 v[68:71], v[156:159], v[208:211], v[148:151]
	v_mfma_f32_16x16x32_bf16 v[136:139], v[184:187], v[196:199], v[136:139]
	v_mfma_f32_16x16x32_bf16 v[140:143], v[184:187], v[200:203], v[140:143]
	v_mfma_f32_16x16x32_bf16 v[144:147], v[184:187], v[204:207], v[144:147]
	v_mfma_f32_16x16x32_bf16 v[148:151], v[184:187], v[208:211], v[152:155]
	v_mfma_f32_16x16x32_bf16 v[152:155], v[192:195], v[196:199], v[160:163]
	v_mfma_f32_16x16x32_bf16 v[156:159], v[192:195], v[200:203], v[164:167]
	v_mfma_f32_16x16x32_bf16 v[160:163], v[192:195], v[204:207], v[176:179]
	v_mfma_f32_16x16x32_bf16 v[164:167], v[192:195], v[208:211], v[180:183]
	global_load_dwordx4 v[94:97], v[102:103], off offset:1216
	s_nop 0
	global_load_dwordx4 v[176:179], v[212:213], off offset:1216
	global_load_dwordx4 v[180:183], v[214:215], off offset:1216
	global_load_dwordx4 v[184:187], v[216:217], off offset:1216
	global_load_dwordx4 v[192:195], v[218:219], off offset:192
	global_load_dwordx4 v[196:199], v[92:93], off offset:192
	global_load_dwordx4 v[200:203], v[88:89], off offset:192
	global_load_dwordx4 v[204:207], v[90:91], off offset:192
	s_load_dwordx2 s[0:1], s[6:7], 0x68
	s_waitcnt vmcnt(0)
	v_mfma_f32_16x16x32_bf16 v[88:91], v[176:179], v[204:207], v[68:71]
	v_mfma_f32_16x16x32_bf16 v[68:71], v[180:183], v[192:195], v[136:139]
	s_waitcnt lgkmcnt(0)
	s_nop 1
	v_lshl_add_u64 v[136:137], v[168:169], 2, s[0:1]
	global_load_dword v137, v[136:137], off
	v_lshl_add_u64 v[138:139], v[0:1], 1, s[8:9]
	v_lshl_add_u32 v1, v171, 2, v173
	ds_read_b32 v2, v1 offset:16640
	v_mfma_f32_16x16x32_bf16 v[132:135], v[94:97], v[192:195], v[24:27]
	s_mov_b64 s[0:1], 0x17a00000
	v_lshl_add_u64 v[138:139], v[138:139], 0, s[0:1]
	v_or_b32_e32 v136, s14, v171
	s_waitcnt lgkmcnt(0)
	v_mul_f32_e32 v2, 0x3fb8aa3b, v2
	v_mfma_f32_16x16x32_bf16 v[128:131], v[94:97], v[196:199], v[28:31]
	v_mfma_f32_16x16x32_bf16 v[124:127], v[94:97], v[200:203], v[32:35]
	v_mfma_f32_16x16x32_bf16 v[120:123], v[94:97], v[204:207], v[36:39]
	v_mfma_f32_16x16x32_bf16 v[92:95], v[176:179], v[200:203], v[64:67]
	v_mfma_f32_16x16x32_bf16 v[64:67], v[180:183], v[196:199], v[140:143]
	s_nop 2
	v_exp_f32_e32 v142, v2
	v_mul_u32_u24_e32 v143, 0x240, v174
	v_lshlrev_b32_e32 v2, 1, v170
	v_add3_u32 v143, v172, v143, v2
	v_mfma_f32_16x16x32_bf16 v[96:99], v[176:179], v[196:199], v[60:63]
	v_fma_f32 v116, v132, v142, v116
	v_mad_i64_i32 v[140:141], s[0:1], v136, s31, v[138:139]
	v_mfma_f32_16x16x32_bf16 v[60:63], v[180:183], v[200:203], v[144:147]
	ds_read_u16 v132, v143 offset:22784
	s_nop 1
	ds_read_u16 v144, v143 offset:22816
	v_lshl_add_u64 v[140:141], v[140:141], 0, v[2:3]
	v_or_b32_e32 v212, 1, v136
	v_mad_i64_i32 v[210:211], s[0:1], v212, s31, v[138:139]
	v_lshl_add_u64 v[210:211], v[210:211], 0, v[2:3]
	global_load_ushort v208, v[210:211], off
	v_or_b32_e32 v212, 2, v136
	v_mad_i64_i32 v[210:211], s[0:1], v212, s31, v[138:139]
	v_lshl_add_u64 v[210:211], v[210:211], 0, v[2:3]
	global_load_ushort v208, v[210:211], off
	v_or_b32_e32 v212, 3, v136
	v_mad_i64_i32 v[210:211], s[0:1], v212, s31, v[138:139]
	v_lshl_add_u64 v[210:211], v[210:211], 0, v[2:3]
	global_load_ushort v208, v[210:211], off
	v_or_b32_e32 v212, 16, v136
	v_mad_i64_i32 v[210:211], s[0:1], v212, s31, v[138:139]
	v_lshl_add_u64 v[210:211], v[210:211], 0, v[2:3]
	global_load_ushort v208, v[210:211], off
	v_or_b32_e32 v212, 17, v136
	v_mad_i64_i32 v[210:211], s[0:1], v212, s31, v[138:139]
	v_lshl_add_u64 v[210:211], v[210:211], 0, v[2:3]
	global_load_ushort v208, v[210:211], off
	v_or_b32_e32 v212, 18, v136
	v_mad_i64_i32 v[210:211], s[0:1], v212, s31, v[138:139]
	v_lshl_add_u64 v[210:211], v[210:211], 0, v[2:3]
; __device__ __forceinline__ float bf2f(u16 h) { return __uint_as_float(((unsigned)h) << 16); }
; __device__ __forceinline__ float siluf_(float x) { return x / (1.f + __expf(-x)); }
; __device__ __forceinline__ void ssd_out_item(KP P, int l, int seq, int c, int g, char* smem) {
;     ...
;     for (int j = 0; j < 4; ++j) {
;       const int lr = mb * 16 + fq * 4 + j;
;       const float ea = __expf(acs[lr]);
;       float ssq = 0.f;
; #pragma unroll
;       for (int nb = 0; nb < 4; ++nb) {
;         const int p = nb * 16 + fr;
;         float y = accy[mb][nb][j] + ea * acco[mb][nb][j] + Dh * bf2f(Xs[lr * 72 + p]);
;         float z = 0.f;
;         if (lr < L) z = bf2f(PROJ[(long)(rb + lr) * NC + OZ + h * 64 + p]);
;         y *= siluf_(z);
;         accy[mb][nb][j] = y;
;         ssq += y * y;
;       }
;       ssq += sx<1>(ssq); ssq += sx<2>(ssq); ssq += sx<4>(ssq); ssq += sx<8>(ssq);
;       if (fr == 0) rsq[wid * 64 + lr] = ssq;
;     }
	global_load_ushort v208, v[210:211], off
	v_or_b32_e32 v212, 19, v136
	v_mad_i64_i32 v[210:211], s[0:1], v212, s31, v[138:139]
	v_lshl_add_u64 v[210:211], v[210:211], 0, v[2:3]
	global_load_ushort v208, v[210:211], off
	v_or_b32_e32 v212, 32, v136
	v_mad_i64_i32 v[210:211], s[0:1], v212, s31, v[138:139]
	v_lshl_add_u64 v[210:211], v[210:211], 0, v[2:3]
	global_load_ushort v208, v[210:211], off
	v_or_b32_e32 v212, 33, v136
	v_mad_i64_i32 v[210:211], s[0:1], v212, s31, v[138:139]
	v_lshl_add_u64 v[210:211], v[210:211], 0, v[2:3]
	global_load_ushort v208, v[210:211], off
	v_or_b32_e32 v212, 34, v136
	v_mad_i64_i32 v[210:211], s[0:1], v212, s31, v[138:139]
	v_lshl_add_u64 v[210:211], v[210:211], 0, v[2:3]
	global_load_ushort v208, v[210:211], off
	v_or_b32_e32 v212, 35, v136
	v_mad_i64_i32 v[210:211], s[0:1], v212, s31, v[138:139]
	v_lshl_add_u64 v[210:211], v[210:211], 0, v[2:3]
	global_load_ushort v208, v[210:211], off
	v_or_b32_e32 v212, 48, v136
	v_mad_i64_i32 v[210:211], s[0:1], v212, s31, v[138:139]
	v_lshl_add_u64 v[210:211], v[210:211], 0, v[2:3]
	global_load_ushort v208, v[210:211], off
	v_or_b32_e32 v212, 49, v136
	v_mad_i64_i32 v[210:211], s[0:1], v212, s31, v[138:139]
	v_lshl_add_u64 v[210:211], v[210:211], 0, v[2:3]
	global_load_ushort v208, v[210:211], off
	v_or_b32_e32 v212, 50, v136
	v_mad_i64_i32 v[210:211], s[0:1], v212, s31, v[138:139]
	v_lshl_add_u64 v[210:211], v[210:211], 0, v[2:3]
	global_load_ushort v208, v[210:211], off
	v_or_b32_e32 v212, 51, v136
	v_mad_i64_i32 v[210:211], s[0:1], v212, s31, v[138:139]
	v_lshl_add_u64 v[210:211], v[210:211], 0, v[2:3]
	global_load_ushort v208, v[210:211], off
	v_fma_f32 v112, v128, v142, v112
	v_mfma_f32_16x16x32_bf16 v[100:103], v[176:179], v[192:195], v[56:59]
	s_waitcnt lgkmcnt(1)
	v_lshlrev_b32_e32 v132, 16, v132
	v_fma_f32 v108, v124, v142, v108
	v_fma_f32 v104, v120, v142, v104
	v_mfma_f32_16x16x32_bf16 v[56:59], v[180:183], v[204:207], v[148:151]
	s_waitcnt vmcnt(0)
	v_fmac_f32_e32 v116, v137, v132
	global_load_ushort v132, v[140:141], off
	v_mfma_f32_16x16x32_bf16 v[36:39], v[184:187], v[192:195], v[152:155]
	global_load_ushort v176, v[140:141], off offset:32
	global_load_ushort v177, v[140:141], off offset:64
	global_load_ushort v178, v[140:141], off offset:96
	s_waitcnt vmcnt(0)
	v_lshlrev_b32_e32 v132, 16, v132
	v_mul_f32_e32 v145, 0xbfb8aa3b, v132
	v_exp_f32_e32 v145, v145
	v_mfma_f32_16x16x32_bf16 v[32:35], v[184:187], v[196:199], v[156:159]
	v_add_f32_e32 v145, 1.0, v145
	v_div_scale_f32 v146, s[0:1], v145, v145, v132
	v_rcp_f32_e32 v147, v146
	v_mfma_f32_16x16x32_bf16 v[28:31], v[184:187], v[200:203], v[160:163]
	v_fma_f32 v148, -v146, v147, 1.0
	v_fmac_f32_e32 v147, v148, v147
	v_div_scale_f32 v148, vcc, v132, v145, v132
	v_mul_f32_e32 v149, v148, v147
	v_fma_f32 v150, -v146, v149, v148
	v_fmac_f32_e32 v149, v150, v147
	v_fma_f32 v146, -v146, v149, v148
	v_div_fmas_f32 v146, v146, v147, v149
	v_div_fixup_f32 v132, v146, v145, v132
	v_mul_f32_e32 v132, v116, v132
	s_waitcnt lgkmcnt(0)
	v_lshlrev_b32_e32 v116, 16, v144
	v_fmac_f32_e32 v112, v137, v116
	v_mov_b32_e32 v116, v176
	v_mfma_f32_16x16x32_bf16 v[24:27], v[184:187], v[204:207], v[164:167]
	v_lshlrev_b32_e32 v116, 16, v116
	v_mul_f32_e32 v128, 0xbfb8aa3b, v116
	v_exp_f32_e32 v128, v128
	s_nop 0
	v_add_f32_e32 v128, 1.0, v128
	v_div_scale_f32 v144, s[0:1], v128, v128, v116
	v_rcp_f32_e32 v145, v144
	s_nop 0
	v_fma_f32 v146, -v144, v145, 1.0
	v_fmac_f32_e32 v145, v146, v145
	v_div_scale_f32 v146, vcc, v116, v128, v116
	v_mul_f32_e32 v147, v146, v145
	v_fma_f32 v148, -v144, v147, v146
	v_fmac_f32_e32 v147, v148, v145
	v_fma_f32 v144, -v144, v147, v146
	v_div_fmas_f32 v144, v144, v145, v147
	v_div_fixup_f32 v116, v144, v128, v116
	v_mul_f32_e32 v128, v112, v116
	ds_read_u16 v116, v143 offset:22848
	v_mul_f32_e32 v112, v128, v128
	v_fmac_f32_e32 v112, v132, v132
	s_waitcnt lgkmcnt(0)
	v_lshlrev_b32_e32 v116, 16, v116
	v_fmac_f32_e32 v108, v137, v116
	v_mov_b32_e32 v116, v177
	v_lshlrev_b32_e32 v116, 16, v116
	v_mul_f32_e32 v124, 0xbfb8aa3b, v116
	v_exp_f32_e32 v124, v124
	s_nop 0
	v_add_f32_e32 v124, 1.0, v124
	v_div_scale_f32 v144, s[0:1], v124, v124, v116
	v_rcp_f32_e32 v145, v144
	s_nop 0
	v_fma_f32 v146, -v144, v145, 1.0
	v_fmac_f32_e32 v145, v146, v145
	v_div_scale_f32 v146, vcc, v116, v124, v116
	v_mul_f32_e32 v147, v146, v145
	v_fma_f32 v148, -v144, v147, v146
	v_fmac_f32_e32 v147, v148, v145
	v_fma_f32 v144, -v144, v147, v146
	v_div_fmas_f32 v144, v144, v145, v147
	v_div_fixup_f32 v116, v144, v124, v116
	v_mul_f32_e32 v124, v108, v116
	ds_read_u16 v108, v143 offset:22880
	v_fmac_f32_e32 v112, v124, v124
	s_waitcnt lgkmcnt(0)
	v_lshlrev_b32_e32 v108, 16, v108
	v_fmac_f32_e32 v104, v137, v108
	v_mov_b32_e32 v108, v178
	v_lshlrev_b32_e32 v108, 16, v108
	v_mul_f32_e32 v116, 0xbfb8aa3b, v108
	v_exp_f32_e32 v116, v116
	s_nop 0
	v_add_f32_e32 v116, 1.0, v116
	v_div_scale_f32 v120, s[0:1], v116, v116, v108
	v_rcp_f32_e32 v140, v120
	s_nop 0
	v_fma_f32 v141, -v120, v140, 1.0
	v_fmac_f32_e32 v140, v141, v140
	v_div_scale_f32 v141, vcc, v108, v116, v108
	v_mul_f32_e32 v142, v141, v140
	v_fma_f32 v143, -v120, v142, v141
	v_fmac_f32_e32 v142, v143, v140
	v_fma_f32 v120, -v120, v142, v141
	v_div_fmas_f32 v120, v120, v140, v142
	v_div_fixup_f32 v108, v120, v116, v108
	v_mul_f32_e32 v120, v104, v108
	v_fmac_f32_e32 v112, v120, v120
	ds_swizzle_b32 v104, v112 offset:swizzle(SWAP,1)
	s_waitcnt lgkmcnt(0)
	v_add_f32_e32 v104, v112, v104
	ds_swizzle_b32 v108, v104 offset:swizzle(SWAP,2)
	s_waitcnt lgkmcnt(0)
	v_add_f32_e32 v104, v104, v108
	ds_swizzle_b32 v108, v104 offset:swizzle(SWAP,4)
	s_waitcnt lgkmcnt(0)
	v_add_f32_e32 v104, v104, v108
	ds_swizzle_b32 v108, v104 offset:swizzle(SWAP,8)
	s_and_saveexec_b64 s[0:1], s[4:5]
	s_cbranch_execz .LBB0_1010
	s_waitcnt lgkmcnt(0)
	v_add_f32_e32 v104, v104, v108
	ds_write_b32 v1, v104 offset:20736

; __device__ __forceinline__ int gdim() { int g = gridDim.x; asm volatile("" : "+s"(g)); return g; }
; #define SK_LOAD(KK) do { rb = *(const uint4*)(bp + (KK)); \
;     if constexpr (AF32) { fa[0] = *(const float4*)(fp0 + (KK)); fa[1] = *(const float4*)(fp0 + (KK) + 4); \
;                           fa[2] = *(const float4*)(fp1 + (KK)); fa[3] = *(const float4*)(fp1 + (KK) + 4); } \
;     else { ra0 = *(const uint4*)(ap0 + (KK)); ra1 = *(const uint4*)(ap1 + (KK)); } } while (0)
; template <bool AF32>
; __device__ __forceinline__ void skinny_gemm(const void* __restrict__ Av, long lda, const u16* __restrict__ Bt, long ldb, int kb, int ke,
;                                             f32x4* acc, char* smem, int tid) {
;     ...
;   SK_LOAD(kb);
;   for (int k0 = kb; k0 < ke; k0 += 64) {
;     if constexpr (AF32) {
;       float f0[8] = {fa[0].x, fa[0].y, fa[0].z, fa[0].w, fa[1].x, fa[1].y, fa[1].z, fa[1].w};
;       float f1[8] = {fa[2].x, fa[2].y, fa[2].z, fa[2].w, fa[3].x, fa[3].y, fa[3].z, fa[3].w};
;       ra0 = pack8(f0); ra1 = pack8(f1);
;     }
;     *(uint4*)(As + r0 * 72 + v0 * 8) = ra0;
;     *(uint4*)(As + (r0 + 64) * 72 + v0 * 8) = ra1;
;     *(uint4*)(Bs + r0 * 72 + v0 * 8) = rb;
;     __syncthreads();
;     if (k0 + 64 < ke) SK_LOAD(k0 + 64);
; #pragma unroll
;     for (int ks = 0; ks < 2; ++ks) {
;       const bf16x8 af = *(const bf16x8*)(As + (wid * 16 + fr) * 72 + ks * 32 + fq * 8);
; #pragma unroll
;       for (int nb = 0; nb < 4; ++nb) {
;         const bf16x8 bf = *(const bf16x8*)(Bs + (nb * 16 + fr) * 72 + ks * 32 + fq * 8);
;         acc[nb] = __builtin_amdgcn_mfma_f32_16x16x32_bf16(af, bf, acc[nb], 0, 0, 0);
;       }
;     }
;     __syncthreads();
;   }
; __global__ void __launch_bounds__(512) mega(Params Pk) {
;     ...
;       for (int tk = pb; tk < 128; tk += gdim()) {
;         f32x4 acc[4] = {};
;         skinny_gemm<false>(XN + (long)NP * D, D, W1T + (long)tk * 64 * D, D, 0, D, acc, smem, tid_);
.LBB0_1261:
	s_ashr_i32 s7, s6, 31
	s_lshl_b64 s[0:1], s[6:7], 18
	v_lshl_add_u64 v[8:9], v[0:1], 0, s[0:1]
	v_mov_b64_e32 v[196:197], v[8:9]
	global_load_dwordx4 v[16:19], v[38:39], off
	global_load_dwordx4 v[12:15], v[36:37], off
	s_nop 0
	global_load_dwordx4 v[8:11], v[8:9], off
	v_readlane_b32 s8, v251, 19
	v_readlane_b32 s9, v251, 20
	s_add_u32 s8, s8, s0
	v_mov_b32_e32 v32, 0
	s_addc_u32 s9, 0, s1
	s_movk_i32 s0, 0xffc0
	s_waitcnt vmcnt(11)
	v_mov_b64_e32 v[52:53], v[50:51]
	v_mov_b32_e32 v33, v32
	v_mov_b32_e32 v34, v32
	v_mov_b32_e32 v35, v32
	v_mov_b32_e32 v28, v32
	v_mov_b32_e32 v29, v32
	v_mov_b32_e32 v30, v32
	v_mov_b32_e32 v31, v32
	v_mov_b32_e32 v24, v32
	v_mov_b32_e32 v25, v32
	v_mov_b32_e32 v26, v32
	v_mov_b32_e32 v27, v32
	v_mov_b32_e32 v20, v32
	v_mov_b32_e32 v21, v32
	v_mov_b32_e32 v22, v32
	v_mov_b32_e32 v23, v32
	v_mov_b64_e32 v[192:193], v[36:37]
	v_mov_b64_e32 v[194:195], v[38:39]
	v_mov_b32_e32 v198, 0x80
	v_mov_b32_e32 v199, 0
	s_mov_b32 s0, 0
	v_lshl_add_u64 v[194:195], v[194:195], 0, v[198:199]
	v_lshl_add_u64 v[192:193], v[192:193], 0, v[198:199]
	v_lshl_add_u64 v[196:197], v[196:197], 0, v[198:199]
	global_load_dwordx4 v[62:65], v[194:195], off
	global_load_dwordx4 v[58:61], v[192:193], off
	global_load_dwordx4 v[66:69], v[196:197], off
	v_lshl_add_u64 v[194:195], v[194:195], 0, v[198:199]
	v_lshl_add_u64 v[192:193], v[192:193], 0, v[198:199]
	v_lshl_add_u64 v[196:197], v[196:197], 0, v[198:199]
	global_load_dwordx4 v[74:77], v[194:195], off
	global_load_dwordx4 v[70:73], v[192:193], off
	global_load_dwordx4 v[78:81], v[196:197], off
.Lsk10_loop:
	v_lshl_add_u64 v[194:195], v[194:195], 0, v[198:199]
	v_lshl_add_u64 v[192:193], v[192:193], 0, v[198:199]
	v_lshl_add_u64 v[196:197], v[196:197], 0, v[198:199]
	global_load_dwordx4 v[86:89], v[194:195], off
	global_load_dwordx4 v[82:85], v[192:193], off
	global_load_dwordx4 v[90:93], v[196:197], off
	s_waitcnt vmcnt(9)
	ds_write_b128 v57, v[12:15]
	ds_write_b128 v2, v[16:19]
	ds_write_b128 v57, v[8:11] offset:18432
	s_waitcnt lgkmcnt(0)
	s_barrier
	ds_read_b128 v[208:211], v40
	ds_read_b128 v[216:219], v41 offset:18432
	ds_read_b128 v[220:223], v41 offset:20736
	ds_read_b128 v[234:237], v41 offset:23040
	ds_read_b128 v[238:241], v41 offset:25344
	ds_read_b128 v[212:215], v40 offset:64
	ds_read_b128 v[242:245], v41 offset:18496
	ds_read_b128 v[246:249], v41 offset:20800
	ds_read_b128 v[200:203], v41 offset:23104
	ds_read_b128 v[204:207], v41 offset:25408
	s_waitcnt lgkmcnt(8)
	v_mfma_f32_16x16x32_bf16 v[32:35], v[208:211], v[216:219], v[32:35]
	s_waitcnt lgkmcnt(7)
	v_mfma_f32_16x16x32_bf16 v[28:31], v[208:211], v[220:223], v[28:31]
	s_waitcnt lgkmcnt(6)
	v_mfma_f32_16x16x32_bf16 v[24:27], v[208:211], v[234:237], v[24:27]
	s_waitcnt lgkmcnt(5)
	v_mfma_f32_16x16x32_bf16 v[20:23], v[208:211], v[238:241], v[20:23]
	s_waitcnt lgkmcnt(3)
	v_mfma_f32_16x16x32_bf16 v[32:35], v[212:215], v[242:245], v[32:35]
	s_waitcnt lgkmcnt(2)
	v_mfma_f32_16x16x32_bf16 v[28:31], v[212:215], v[246:249], v[28:31]
	s_waitcnt lgkmcnt(1)
	v_mfma_f32_16x16x32_bf16 v[24:27], v[212:215], v[200:203], v[24:27]
	s_waitcnt lgkmcnt(0)
	s_barrier
	v_mfma_f32_16x16x32_bf16 v[20:23], v[212:215], v[204:207], v[20:23]
	v_lshl_add_u64 v[194:195], v[194:195], 0, v[198:199]
	v_lshl_add_u64 v[192:193], v[192:193], 0, v[198:199]
	v_lshl_add_u64 v[196:197], v[196:197], 0, v[198:199]
	global_load_dwordx4 v[16:19], v[194:195], off
	global_load_dwordx4 v[12:15], v[192:193], off
	global_load_dwordx4 v[8:11], v[196:197], off
	s_waitcnt vmcnt(9)
	ds_write_b128 v57, v[58:61]
	ds_write_b128 v2, v[62:65]
	ds_write_b128 v57, v[66:69] offset:18432
	s_waitcnt lgkmcnt(0)
	s_barrier
	ds_read_b128 v[208:211], v40
	ds_read_b128 v[216:219], v41 offset:18432
	ds_read_b128 v[220:223], v41 offset:20736
	ds_read_b128 v[234:237], v41 offset:23040
	ds_read_b128 v[238:241], v41 offset:25344
	ds_read_b128 v[212:215], v40 offset:64
	ds_read_b128 v[242:245], v41 offset:18496
	ds_read_b128 v[246:249], v41 offset:20800
	ds_read_b128 v[200:203], v41 offset:23104
	ds_read_b128 v[204:207], v41 offset:25408
	s_waitcnt lgkmcnt(8)
	v_mfma_f32_16x16x32_bf16 v[32:35], v[208:211], v[216:219], v[32:35]
	s_waitcnt lgkmcnt(7)
	v_mfma_f32_16x16x32_bf16 v[28:31], v[208:211], v[220:223], v[28:31]
	s_waitcnt lgkmcnt(6)
	v_mfma_f32_16x16x32_bf16 v[24:27], v[208:211], v[234:237], v[24:27]
	s_waitcnt lgkmcnt(5)
	v_mfma_f32_16x16x32_bf16 v[20:23], v[208:211], v[238:241], v[20:23]
	s_waitcnt lgkmcnt(3)
	v_mfma_f32_16x16x32_bf16 v[32:35], v[212:215], v[242:245], v[32:35]
	s_waitcnt lgkmcnt(2)
	v_mfma_f32_16x16x32_bf16 v[28:31], v[212:215], v[246:249], v[28:31]
	s_waitcnt lgkmcnt(1)
	v_mfma_f32_16x16x32_bf16 v[24:27], v[212:215], v[200:203], v[24:27]
	s_waitcnt lgkmcnt(0)
	s_barrier
	v_mfma_f32_16x16x32_bf16 v[20:23], v[212:215], v[204:207], v[20:23]
	v_lshl_add_u64 v[194:195], v[194:195], 0, v[198:199]
	v_lshl_add_u64 v[192:193], v[192:193], 0, v[198:199]
	v_lshl_add_u64 v[196:197], v[196:197], 0, v[198:199]
	global_load_dwordx4 v[62:65], v[194:195], off
	global_load_dwordx4 v[58:61], v[192:193], off
	global_load_dwordx4 v[66:69], v[196:197], off
	s_waitcnt vmcnt(9)
	ds_write_b128 v57, v[70:73]
	ds_write_b128 v2, v[74:77]
	ds_write_b128 v57, v[78:81] offset:18432
	s_waitcnt lgkmcnt(0)
	s_barrier
; #define SK_LOAD(KK) do { rb = *(const uint4*)(bp + (KK)); \
;     if constexpr (AF32) { fa[0] = *(const float4*)(fp0 + (KK)); fa[1] = *(const float4*)(fp0 + (KK) + 4); \
;                           fa[2] = *(const float4*)(fp1 + (KK)); fa[3] = *(const float4*)(fp1 + (KK) + 4); } \
;     else { ra0 = *(const uint4*)(ap0 + (KK)); ra1 = *(const uint4*)(ap1 + (KK)); } } while (0)
; template <bool AF32>
; __device__ __forceinline__ void skinny_gemm(const void* __restrict__ Av, long lda, const u16* __restrict__ Bt, long ldb, int kb, int ke,
;                                             f32x4* acc, char* smem, int tid) {
;     ...
;   for (int k0 = kb; k0 < ke; k0 += 64) {
;     if constexpr (AF32) {
;       float f0[8] = {fa[0].x, fa[0].y, fa[0].z, fa[0].w, fa[1].x, fa[1].y, fa[1].z, fa[1].w};
;       float f1[8] = {fa[2].x, fa[2].y, fa[2].z, fa[2].w, fa[3].x, fa[3].y, fa[3].z, fa[3].w};
;       ra0 = pack8(f0); ra1 = pack8(f1);
;     }
;     *(uint4*)(As + r0 * 72 + v0 * 8) = ra0;
;     *(uint4*)(As + (r0 + 64) * 72 + v0 * 8) = ra1;
;     *(uint4*)(Bs + r0 * 72 + v0 * 8) = rb;
;     __syncthreads();
;     if (k0 + 64 < ke) SK_LOAD(k0 + 64);
; #pragma unroll
;     for (int ks = 0; ks < 2; ++ks) {
;       const bf16x8 af = *(const bf16x8*)(As + (wid * 16 + fr) * 72 + ks * 32 + fq * 8);
; #pragma unroll
;       for (int nb = 0; nb < 4; ++nb) {
;         const bf16x8 bf = *(const bf16x8*)(Bs + (nb * 16 + fr) * 72 + ks * 32 + fq * 8);
;         acc[nb] = __builtin_amdgcn_mfma_f32_16x16x32_bf16(af, bf, acc[nb], 0, 0, 0);
;       }
;     }
;     __syncthreads();
;   }
	ds_read_b128 v[208:211], v40
	ds_read_b128 v[216:219], v41 offset:18432
	ds_read_b128 v[220:223], v41 offset:20736
	ds_read_b128 v[234:237], v41 offset:23040
	ds_read_b128 v[238:241], v41 offset:25344
	ds_read_b128 v[212:215], v40 offset:64
	ds_read_b128 v[242:245], v41 offset:18496
	ds_read_b128 v[246:249], v41 offset:20800
	ds_read_b128 v[200:203], v41 offset:23104
	ds_read_b128 v[204:207], v41 offset:25408
	s_waitcnt lgkmcnt(8)
	v_mfma_f32_16x16x32_bf16 v[32:35], v[208:211], v[216:219], v[32:35]
	s_waitcnt lgkmcnt(7)
	v_mfma_f32_16x16x32_bf16 v[28:31], v[208:211], v[220:223], v[28:31]
	s_waitcnt lgkmcnt(6)
	v_mfma_f32_16x16x32_bf16 v[24:27], v[208:211], v[234:237], v[24:27]
	s_waitcnt lgkmcnt(5)
	v_mfma_f32_16x16x32_bf16 v[20:23], v[208:211], v[238:241], v[20:23]
	s_waitcnt lgkmcnt(3)
	v_mfma_f32_16x16x32_bf16 v[32:35], v[212:215], v[242:245], v[32:35]
	s_waitcnt lgkmcnt(2)
	v_mfma_f32_16x16x32_bf16 v[28:31], v[212:215], v[246:249], v[28:31]
	s_waitcnt lgkmcnt(1)
	v_mfma_f32_16x16x32_bf16 v[24:27], v[212:215], v[200:203], v[24:27]
	s_waitcnt lgkmcnt(0)
	s_barrier
	v_mfma_f32_16x16x32_bf16 v[20:23], v[212:215], v[204:207], v[20:23]
	v_lshl_add_u64 v[194:195], v[194:195], 0, v[198:199]
	v_lshl_add_u64 v[192:193], v[192:193], 0, v[198:199]
	v_lshl_add_u64 v[196:197], v[196:197], 0, v[198:199]
	global_load_dwordx4 v[74:77], v[194:195], off
	global_load_dwordx4 v[70:73], v[192:193], off
	global_load_dwordx4 v[78:81], v[196:197], off
	s_waitcnt vmcnt(9)
	ds_write_b128 v57, v[82:85]
	ds_write_b128 v2, v[86:89]
	ds_write_b128 v57, v[90:93] offset:18432
	s_waitcnt lgkmcnt(0)
	s_barrier
	ds_read_b128 v[208:211], v40
	ds_read_b128 v[216:219], v41 offset:18432
	ds_read_b128 v[220:223], v41 offset:20736
	ds_read_b128 v[234:237], v41 offset:23040
	ds_read_b128 v[238:241], v41 offset:25344
	ds_read_b128 v[212:215], v40 offset:64
	ds_read_b128 v[242:245], v41 offset:18496
	ds_read_b128 v[246:249], v41 offset:20800
	ds_read_b128 v[200:203], v41 offset:23104
	ds_read_b128 v[204:207], v41 offset:25408
	s_waitcnt lgkmcnt(8)
	v_mfma_f32_16x16x32_bf16 v[32:35], v[208:211], v[216:219], v[32:35]
	s_waitcnt lgkmcnt(7)
	v_mfma_f32_16x16x32_bf16 v[28:31], v[208:211], v[220:223], v[28:31]
	s_waitcnt lgkmcnt(6)
	v_mfma_f32_16x16x32_bf16 v[24:27], v[208:211], v[234:237], v[24:27]
	s_waitcnt lgkmcnt(5)
	v_mfma_f32_16x16x32_bf16 v[20:23], v[208:211], v[238:241], v[20:23]
	s_waitcnt lgkmcnt(3)
	v_mfma_f32_16x16x32_bf16 v[32:35], v[212:215], v[242:245], v[32:35]
	s_waitcnt lgkmcnt(2)
	v_mfma_f32_16x16x32_bf16 v[28:31], v[212:215], v[246:249], v[28:31]
	s_waitcnt lgkmcnt(1)
	v_mfma_f32_16x16x32_bf16 v[24:27], v[212:215], v[200:203], v[24:27]
	s_waitcnt lgkmcnt(0)
	s_barrier
	v_mfma_f32_16x16x32_bf16 v[20:23], v[212:215], v[204:207], v[20:23]
	s_add_i32 s0, s0, 4
	s_cmp_lt_u32 s0, 28
	s_cbranch_scc1 .Lsk10_loop
	v_lshl_add_u64 v[194:195], v[194:195], 0, v[198:199]
	v_lshl_add_u64 v[192:193], v[192:193], 0, v[198:199]
	v_lshl_add_u64 v[196:197], v[196:197], 0, v[198:199]
	global_load_dwordx4 v[86:89], v[194:195], off
	global_load_dwordx4 v[82:85], v[192:193], off
	global_load_dwordx4 v[90:93], v[196:197], off
	s_waitcnt vmcnt(9)
	ds_write_b128 v57, v[12:15]
	ds_write_b128 v2, v[16:19]
	ds_write_b128 v57, v[8:11] offset:18432
	s_waitcnt lgkmcnt(0)
	s_barrier
	ds_read_b128 v[208:211], v40
	ds_read_b128 v[216:219], v41 offset:18432
	ds_read_b128 v[220:223], v41 offset:20736
	ds_read_b128 v[234:237], v41 offset:23040
	ds_read_b128 v[238:241], v41 offset:25344
	ds_read_b128 v[212:215], v40 offset:64
	ds_read_b128 v[242:245], v41 offset:18496
	ds_read_b128 v[246:249], v41 offset:20800
	ds_read_b128 v[200:203], v41 offset:23104
	ds_read_b128 v[204:207], v41 offset:25408
	s_waitcnt lgkmcnt(8)
	v_mfma_f32_16x16x32_bf16 v[32:35], v[208:211], v[216:219], v[32:35]
	s_waitcnt lgkmcnt(7)
	v_mfma_f32_16x16x32_bf16 v[28:31], v[208:211], v[220:223], v[28:31]
	s_waitcnt lgkmcnt(6)
	v_mfma_f32_16x16x32_bf16 v[24:27], v[208:211], v[234:237], v[24:27]
	s_waitcnt lgkmcnt(5)
	v_mfma_f32_16x16x32_bf16 v[20:23], v[208:211], v[238:241], v[20:23]
	s_waitcnt lgkmcnt(3)
	v_mfma_f32_16x16x32_bf16 v[32:35], v[212:215], v[242:245], v[32:35]
	s_waitcnt lgkmcnt(2)
	v_mfma_f32_16x16x32_bf16 v[28:31], v[212:215], v[246:249], v[28:31]
	s_waitcnt lgkmcnt(1)
	v_mfma_f32_16x16x32_bf16 v[24:27], v[212:215], v[200:203], v[24:27]
	s_waitcnt lgkmcnt(0)
	s_barrier
; #define SK_LOAD(KK) do { rb = *(const uint4*)(bp + (KK)); \
;     if constexpr (AF32) { fa[0] = *(const float4*)(fp0 + (KK)); fa[1] = *(const float4*)(fp0 + (KK) + 4); \
;                           fa[2] = *(const float4*)(fp1 + (KK)); fa[3] = *(const float4*)(fp1 + (KK) + 4); } \
;     else { ra0 = *(const uint4*)(ap0 + (KK)); ra1 = *(const uint4*)(ap1 + (KK)); } } while (0)
; template <bool AF32>
; __device__ __forceinline__ void skinny_gemm(const void* __restrict__ Av, long lda, const u16* __restrict__ Bt, long ldb, int kb, int ke,
;                                             f32x4* acc, char* smem, int tid) {
;     ...
;   for (int k0 = kb; k0 < ke; k0 += 64) {
;     if constexpr (AF32) {
;       float f0[8] = {fa[0].x, fa[0].y, fa[0].z, fa[0].w, fa[1].x, fa[1].y, fa[1].z, fa[1].w};
;       float f1[8] = {fa[2].x, fa[2].y, fa[2].z, fa[2].w, fa[3].x, fa[3].y, fa[3].z, fa[3].w};
;       ra0 = pack8(f0); ra1 = pack8(f1);
;     }
;     *(uint4*)(As + r0 * 72 + v0 * 8) = ra0;
;     *(uint4*)(As + (r0 + 64) * 72 + v0 * 8) = ra1;
;     *(uint4*)(Bs + r0 * 72 + v0 * 8) = rb;
;     __syncthreads();
;     if (k0 + 64 < ke) SK_LOAD(k0 + 64);
; #pragma unroll
;     for (int ks = 0; ks < 2; ++ks) {
;       const bf16x8 af = *(const bf16x8*)(As + (wid * 16 + fr) * 72 + ks * 32 + fq * 8);
; #pragma unroll
;       for (int nb = 0; nb < 4; ++nb) {
;         const bf16x8 bf = *(const bf16x8*)(Bs + (nb * 16 + fr) * 72 + ks * 32 + fq * 8);
;         acc[nb] = __builtin_amdgcn_mfma_f32_16x16x32_bf16(af, bf, acc[nb], 0, 0, 0);
;       }
;     }
;     __syncthreads();
;   }
	v_mfma_f32_16x16x32_bf16 v[20:23], v[212:215], v[204:207], v[20:23]
	s_waitcnt vmcnt(6)
	ds_write_b128 v57, v[58:61]
	ds_write_b128 v2, v[62:65]
	ds_write_b128 v57, v[66:69] offset:18432
	s_waitcnt lgkmcnt(0)
	s_barrier
	ds_read_b128 v[208:211], v40
	ds_read_b128 v[216:219], v41 offset:18432
	ds_read_b128 v[220:223], v41 offset:20736
	ds_read_b128 v[234:237], v41 offset:23040
	ds_read_b128 v[238:241], v41 offset:25344
	ds_read_b128 v[212:215], v40 offset:64
	ds_read_b128 v[242:245], v41 offset:18496
	ds_read_b128 v[246:249], v41 offset:20800
	ds_read_b128 v[200:203], v41 offset:23104
	ds_read_b128 v[204:207], v41 offset:25408
	s_waitcnt lgkmcnt(8)
	v_mfma_f32_16x16x32_bf16 v[32:35], v[208:211], v[216:219], v[32:35]
	s_waitcnt lgkmcnt(7)
	v_mfma_f32_16x16x32_bf16 v[28:31], v[208:211], v[220:223], v[28:31]
	s_waitcnt lgkmcnt(6)
	v_mfma_f32_16x16x32_bf16 v[24:27], v[208:211], v[234:237], v[24:27]
	s_waitcnt lgkmcnt(5)
	v_mfma_f32_16x16x32_bf16 v[20:23], v[208:211], v[238:241], v[20:23]
	s_waitcnt lgkmcnt(3)
	v_mfma_f32_16x16x32_bf16 v[32:35], v[212:215], v[242:245], v[32:35]
	s_waitcnt lgkmcnt(2)
	v_mfma_f32_16x16x32_bf16 v[28:31], v[212:215], v[246:249], v[28:31]
	s_waitcnt lgkmcnt(1)
	v_mfma_f32_16x16x32_bf16 v[24:27], v[212:215], v[200:203], v[24:27]
	s_waitcnt lgkmcnt(0)
	s_barrier
	v_mfma_f32_16x16x32_bf16 v[20:23], v[212:215], v[204:207], v[20:23]
	s_waitcnt vmcnt(3)
	ds_write_b128 v57, v[70:73]
	ds_write_b128 v2, v[74:77]
	ds_write_b128 v57, v[78:81] offset:18432
	s_waitcnt lgkmcnt(0)
	s_barrier
	ds_read_b128 v[208:211], v40
	ds_read_b128 v[216:219], v41 offset:18432
	ds_read_b128 v[220:223], v41 offset:20736
	ds_read_b128 v[234:237], v41 offset:23040
	ds_read_b128 v[238:241], v41 offset:25344
	ds_read_b128 v[212:215], v40 offset:64
	ds_read_b128 v[242:245], v41 offset:18496
	ds_read_b128 v[246:249], v41 offset:20800
	ds_read_b128 v[200:203], v41 offset:23104
	ds_read_b128 v[204:207], v41 offset:25408
	s_waitcnt lgkmcnt(8)
	v_mfma_f32_16x16x32_bf16 v[32:35], v[208:211], v[216:219], v[32:35]
	s_waitcnt lgkmcnt(7)
	v_mfma_f32_16x16x32_bf16 v[28:31], v[208:211], v[220:223], v[28:31]
	s_waitcnt lgkmcnt(6)
	v_mfma_f32_16x16x32_bf16 v[24:27], v[208:211], v[234:237], v[24:27]
	s_waitcnt lgkmcnt(5)
	v_mfma_f32_16x16x32_bf16 v[20:23], v[208:211], v[238:241], v[20:23]
	s_waitcnt lgkmcnt(3)
	v_mfma_f32_16x16x32_bf16 v[32:35], v[212:215], v[242:245], v[32:35]
	s_waitcnt lgkmcnt(2)
	v_mfma_f32_16x16x32_bf16 v[28:31], v[212:215], v[246:249], v[28:31]
	s_waitcnt lgkmcnt(1)
	v_mfma_f32_16x16x32_bf16 v[24:27], v[212:215], v[200:203], v[24:27]
	s_waitcnt lgkmcnt(0)
	s_barrier
	v_mfma_f32_16x16x32_bf16 v[20:23], v[212:215], v[204:207], v[20:23]
	s_waitcnt vmcnt(0)
	ds_write_b128 v57, v[82:85]
	ds_write_b128 v2, v[86:89]
	ds_write_b128 v57, v[90:93] offset:18432
	s_waitcnt lgkmcnt(0)
	s_barrier
	ds_read_b128 v[208:211], v40
	ds_read_b128 v[216:219], v41 offset:18432
	ds_read_b128 v[220:223], v41 offset:20736
	ds_read_b128 v[234:237], v41 offset:23040
	ds_read_b128 v[238:241], v41 offset:25344
	ds_read_b128 v[212:215], v40 offset:64
	ds_read_b128 v[242:245], v41 offset:18496
	ds_read_b128 v[246:249], v41 offset:20800
	ds_read_b128 v[200:203], v41 offset:23104
	ds_read_b128 v[204:207], v41 offset:25408
	s_waitcnt lgkmcnt(8)
	v_mfma_f32_16x16x32_bf16 v[32:35], v[208:211], v[216:219], v[32:35]
	s_waitcnt lgkmcnt(7)
	v_mfma_f32_16x16x32_bf16 v[28:31], v[208:211], v[220:223], v[28:31]
	s_waitcnt lgkmcnt(6)
	v_mfma_f32_16x16x32_bf16 v[24:27], v[208:211], v[234:237], v[24:27]
	s_waitcnt lgkmcnt(5)
	v_mfma_f32_16x16x32_bf16 v[20:23], v[208:211], v[238:241], v[20:23]
	s_waitcnt lgkmcnt(3)
	v_mfma_f32_16x16x32_bf16 v[32:35], v[212:215], v[242:245], v[32:35]
	s_waitcnt lgkmcnt(2)
	v_mfma_f32_16x16x32_bf16 v[28:31], v[212:215], v[246:249], v[28:31]
	s_waitcnt lgkmcnt(1)
	v_mfma_f32_16x16x32_bf16 v[24:27], v[212:215], v[200:203], v[24:27]
	s_waitcnt lgkmcnt(0)
	s_barrier
	v_mfma_f32_16x16x32_bf16 v[20:23], v[212:215], v[204:207], v[20:23]
	s_branch .LBB0_1260
